# compress item: preload all W1T B fragments before the MFMA chain (on top of EpiAct + selected prefetch)
# speedup vs baseline: 1.0027x; 1.0027x over previous
; DI unsigned cvtpk(float lo, float hi) { return pg8::cvt_pk_bf16(lo, hi); }
; DI void compress_item(const Args& a, int l, int item, unsigned char* lds, int tid) {
;     ...
;     const bf16_t* wrow = W1T + (size_t)j * 64 * 2048 + (size_t)r * 2048;
;     float* part = (float*)lds; float* hs = (float*)(lds + 32768);
;     pg8::f32x4 acc[4];
; #pragma unroll
;     for (int ct = 0; ct < 4; ++ct) acc[ct] = (pg8::f32x4){0.f, 0.f, 0.f, 0.f};
; #pragma unroll
;     for (int ks = 0; ks < 8; ++ks) { const int kk = wave * 256 + ks * 32 + kq * 8, li = kk >> 6, d0 = kk & 63; bf16x8 af;
;         if (r < 15) af = *(const bf16x8*)(arow + (size_t)li * ZP + d0);
;         else { const f32x4 p0 = *(const f32x4*)(pe + kk), p1 = *(const f32x4*)(pe + kk + 4); u32x4 w; w.x = cvtpk(p0[0], p0[1]); w.y = cvtpk(p0[2], p0[3]); w.z = cvtpk(p1[0], p1[1]); w.w = cvtpk(p1[2], p1[3]); af = __builtin_bit_cast(bf16x8, w); }
; #pragma unroll
;         for (int ct = 0; ct < 4; ++ct) { const bf16x8 bfr = *(const bf16x8*)(wrow + (size_t)ct * 16 * 2048 + kk); acc[ct] = __builtin_amdgcn_mfma_f32_16x16x32_bf16(af, bfr, acc[ct], 0, 0, 0); } }
.LBB0_309:
	s_or_b64 exec, exec, s[36:37]
	s_lshl_b32 s35, s9, 18
	s_add_u32 s36, s84, s35
	s_addc_u32 s37, s90, 0
	v_lshlrev_b32_e32 v160, 12, v32
	v_lshl_add_u64 v[24:25], s[36:37], 0, v[160:161]
	v_lshl_add_u64 v[16:17], v[20:21], 1, v[24:25]
	s_mov_b32 s100, 0x10000
	s_mov_b32 s101, 0
	v_lshl_add_u64 v[200:201], v[16:17], 0, s[100:101]
	s_mov_b32 s100, 0x20000
	v_lshl_add_u64 v[202:203], v[16:17], 0, s[100:101]
	s_mov_b32 s100, 0x30000
	v_lshl_add_u64 v[204:205], v[16:17], 0, s[100:101]
	global_load_dwordx4 v[56:59], v[16:17], off
	global_load_dwordx4 v[60:63], v[200:201], off
	global_load_dwordx4 v[64:67], v[202:203], off
	global_load_dwordx4 v[68:71], v[204:205], off
	global_load_dwordx4 v[72:75], v[16:17], off offset:64
	global_load_dwordx4 v[76:79], v[200:201], off offset:64
	global_load_dwordx4 v[80:83], v[202:203], off offset:64
	global_load_dwordx4 v[84:87], v[204:205], off offset:64
	global_load_dwordx4 v[88:91], v[16:17], off offset:128
	global_load_dwordx4 v[92:95], v[200:201], off offset:128
	global_load_dwordx4 v[96:99], v[202:203], off offset:128
	global_load_dwordx4 v[100:103], v[204:205], off offset:128
	global_load_dwordx4 v[104:107], v[16:17], off offset:192
	global_load_dwordx4 v[108:111], v[200:201], off offset:192
	global_load_dwordx4 v[112:115], v[202:203], off offset:192
	global_load_dwordx4 v[116:119], v[204:205], off offset:192
	global_load_dwordx4 v[120:123], v[16:17], off offset:256
	global_load_dwordx4 v[124:127], v[200:201], off offset:256
	global_load_dwordx4 v[128:131], v[202:203], off offset:256
	global_load_dwordx4 v[132:135], v[204:205], off offset:256
	global_load_dwordx4 v[136:139], v[16:17], off offset:320
	global_load_dwordx4 v[140:143], v[200:201], off offset:320
	global_load_dwordx4 v[148:151], v[202:203], off offset:320
	global_load_dwordx4 v[152:155], v[204:205], off offset:320
	global_load_dwordx4 v[156:159], v[16:17], off offset:384
	global_load_dwordx4 v[168:171], v[200:201], off offset:384
	global_load_dwordx4 v[172:175], v[202:203], off offset:384
	global_load_dwordx4 v[176:179], v[204:205], off offset:384
	global_load_dwordx4 v[180:183], v[16:17], off offset:448
	global_load_dwordx4 v[184:187], v[200:201], off offset:448
	global_load_dwordx4 v[188:191], v[202:203], off offset:448
	global_load_dwordx4 v[192:195], v[204:205], off offset:448
	s_mov_b32 s35, 0x10000
	v_add_co_u32_e32 v8, vcc, s35, v16
	s_nop 0
	v_addc_co_u32_e32 v9, vcc, 0, v17, vcc
	v_add_co_u32_e32 v12, vcc, 0x20000, v16
	s_nop 0
	v_addc_co_u32_e32 v13, vcc, 0, v17, vcc
	v_add_co_u32_e32 v16, vcc, 0x30000, v16
	s_nop 0
	v_addc_co_u32_e32 v17, vcc, 0, v17, vcc
	v_or_b32_e32 v22, 32, v20
	v_ashrrev_i32_e32 v23, 31, v22
	s_waitcnt vmcnt(0)
	v_mfma_f32_16x16x32_bf16 v[4:7], v[0:3], v[56:59], 0
	v_mfma_f32_16x16x32_bf16 v[8:11], v[0:3], v[60:63], 0
	v_mfma_f32_16x16x32_bf16 v[12:15], v[0:3], v[64:67], 0
	v_mfma_f32_16x16x32_bf16 v[0:3], v[0:3], v[68:71], 0
	s_and_saveexec_b64 s[36:37], s[6:7]
	s_xor_b64 s[36:37], exec, s[36:37]
	s_cbranch_execz .LBB0_311
	v_and_b32_e32 v18, 56, v22
	s_lshl_b32 s35, s8, 2
	v_mov_b32_e32 v16, 0x2230
	v_mad_i64_i32 v[16:17], s[56:57], s35, v16, v[28:29]
	v_lshlrev_b32_e32 v160, 1, v18
	v_lshl_add_u64 v[16:17], v[16:17], 0, v[160:161]
	global_load_dwordx4 v[16:19], v[16:17], off

; DI unsigned cvtpk(float lo, float hi) { return pg8::cvt_pk_bf16(lo, hi); }
; DI void compress_item(const Args& a, int l, int item, unsigned char* lds, int tid) {
;     ...
;     for (int ks = 0; ks < 8; ++ks) { const int kk = wave * 256 + ks * 32 + kq * 8, li = kk >> 6, d0 = kk & 63; bf16x8 af;
;         if (r < 15) af = *(const bf16x8*)(arow + (size_t)li * ZP + d0);
;         else { const f32x4 p0 = *(const f32x4*)(pe + kk), p1 = *(const f32x4*)(pe + kk + 4); u32x4 w; w.x = cvtpk(p0[0], p0[1]); w.y = cvtpk(p0[2], p0[3]); w.z = cvtpk(p1[0], p1[1]); w.w = cvtpk(p1[2], p1[3]); af = __builtin_bit_cast(bf16x8, w); }
; #pragma unroll
;         for (int ct = 0; ct < 4; ++ct) { const bf16x8 bfr = *(const bf16x8*)(wrow + (size_t)ct * 16 * 2048 + kk); acc[ct] = __builtin_amdgcn_mfma_f32_16x16x32_bf16(af, bfr, acc[ct], 0, 0, 0); } }
.LBB0_313:
	s_or_b64 exec, exec, s[36:37]
	v_lshl_add_u64 v[34:35], v[22:23], 1, v[24:25]
	s_or_b32 s35, s34, 64
	s_waitcnt vmcnt(0)
	v_mfma_f32_16x16x32_bf16 v[4:7], v[16:19], v[72:75], v[4:7]
	v_add_co_u32_e32 v20, vcc, 0x10000, v34
	s_nop 1
	v_addc_co_u32_e32 v21, vcc, 0, v35, vcc
	v_mfma_f32_16x16x32_bf16 v[8:11], v[16:19], v[76:79], v[8:11]
	v_add_co_u32_e32 v20, vcc, 0x20000, v34
	s_nop 1
	v_addc_co_u32_e32 v21, vcc, 0, v35, vcc
	v_mfma_f32_16x16x32_bf16 v[12:15], v[16:19], v[80:83], v[12:15]
	v_add_co_u32_e32 v20, vcc, 0x30000, v34
	s_nop 1
	v_addc_co_u32_e32 v21, vcc, 0, v35, vcc
	v_mfma_f32_16x16x32_bf16 v[16:19], v[16:19], v[84:87], v[0:3]
	s_nop 2
	v_or_b32_e32 v0, s35, v26
	v_ashrrev_i32_e32 v1, 31, v0
	s_and_saveexec_b64 s[36:37], s[6:7]
	s_xor_b64 s[36:37], exec, s[36:37]
	s_cbranch_execz .LBB0_315
	s_ashr_i32 s35, s35, 6
	v_mov_b32_e32 v2, 0x2230
	v_mad_i64_i32 v[2:3], s[56:57], s35, v2, v[28:29]
	v_mov_b32_e32 v31, v161
	v_lshl_add_u64 v[2:3], v[2:3], 0, v[30:31]
	global_load_dwordx4 v[20:23], v[2:3], off

; DI unsigned cvtpk(float lo, float hi) { return pg8::cvt_pk_bf16(lo, hi); }
; DI void compress_item(const Args& a, int l, int item, unsigned char* lds, int tid) {
;     ...
;     for (int ks = 0; ks < 8; ++ks) { const int kk = wave * 256 + ks * 32 + kq * 8, li = kk >> 6, d0 = kk & 63; bf16x8 af;
;         if (r < 15) af = *(const bf16x8*)(arow + (size_t)li * ZP + d0);
;         else { const f32x4 p0 = *(const f32x4*)(pe + kk), p1 = *(const f32x4*)(pe + kk + 4); u32x4 w; w.x = cvtpk(p0[0], p0[1]); w.y = cvtpk(p0[2], p0[3]); w.z = cvtpk(p1[0], p1[1]); w.w = cvtpk(p1[2], p1[3]); af = __builtin_bit_cast(bf16x8, w); }
; #pragma unroll
;         for (int ct = 0; ct < 4; ++ct) { const bf16x8 bfr = *(const bf16x8*)(wrow + (size_t)ct * 16 * 2048 + kk); acc[ct] = __builtin_amdgcn_mfma_f32_16x16x32_bf16(af, bfr, acc[ct], 0, 0, 0); } }
.LBB0_317:
	s_or_b64 exec, exec, s[36:37]
	v_lshl_add_u64 v[34:35], v[0:1], 1, v[24:25]
	s_or_b32 s35, s34, 0x60
	s_waitcnt vmcnt(0)
	v_mfma_f32_16x16x32_bf16 v[0:3], v[20:23], v[88:91], v[4:7]
	s_nop 2
	v_add_co_u32_e32 v4, vcc, 0x10000, v34
	s_nop 1
	v_addc_co_u32_e32 v5, vcc, 0, v35, vcc
	v_mfma_f32_16x16x32_bf16 v[4:7], v[20:23], v[92:95], v[8:11]
	s_nop 2
	v_add_co_u32_e32 v8, vcc, 0x20000, v34
	s_nop 1
	v_addc_co_u32_e32 v9, vcc, 0, v35, vcc
	v_mfma_f32_16x16x32_bf16 v[8:11], v[20:23], v[96:99], v[12:15]
	s_nop 2
	v_add_co_u32_e32 v12, vcc, 0x30000, v34
	s_nop 1
	v_addc_co_u32_e32 v13, vcc, 0, v35, vcc
	v_mfma_f32_16x16x32_bf16 v[12:15], v[20:23], v[100:103], v[16:19]
	v_or_b32_e32 v20, s35, v26
	v_ashrrev_i32_e32 v21, 31, v20
	s_and_saveexec_b64 s[36:37], s[6:7]
	s_xor_b64 s[36:37], exec, s[36:37]
	s_cbranch_execz .LBB0_319
	v_and_b32_e32 v18, 56, v20
	s_ashr_i32 s35, s35, 6
	v_mov_b32_e32 v16, 0x2230
	v_mad_i64_i32 v[16:17], s[56:57], s35, v16, v[28:29]
	v_lshlrev_b32_e32 v160, 1, v18
	v_lshl_add_u64 v[16:17], v[16:17], 0, v[160:161]
	global_load_dwordx4 v[16:19], v[16:17], off

; DI unsigned cvtpk(float lo, float hi) { return pg8::cvt_pk_bf16(lo, hi); }
; DI void compress_item(const Args& a, int l, int item, unsigned char* lds, int tid) {
;     ...
;     for (int ks = 0; ks < 8; ++ks) { const int kk = wave * 256 + ks * 32 + kq * 8, li = kk >> 6, d0 = kk & 63; bf16x8 af;
;         if (r < 15) af = *(const bf16x8*)(arow + (size_t)li * ZP + d0);
;         else { const f32x4 p0 = *(const f32x4*)(pe + kk), p1 = *(const f32x4*)(pe + kk + 4); u32x4 w; w.x = cvtpk(p0[0], p0[1]); w.y = cvtpk(p0[2], p0[3]); w.z = cvtpk(p1[0], p1[1]); w.w = cvtpk(p1[2], p1[3]); af = __builtin_bit_cast(bf16x8, w); }
; #pragma unroll
;         for (int ct = 0; ct < 4; ++ct) { const bf16x8 bfr = *(const bf16x8*)(wrow + (size_t)ct * 16 * 2048 + kk); acc[ct] = __builtin_amdgcn_mfma_f32_16x16x32_bf16(af, bfr, acc[ct], 0, 0, 0); } }
.LBB0_321:
	s_or_b64 exec, exec, s[36:37]
	v_lshl_add_u64 v[34:35], v[20:21], 1, v[24:25]
	s_or_b32 s35, s34, 0x80
	s_waitcnt vmcnt(0)
	v_mfma_f32_16x16x32_bf16 v[0:3], v[16:19], v[104:107], v[0:3]
	v_add_co_u32_e32 v20, vcc, 0x10000, v34
	s_nop 1
	v_addc_co_u32_e32 v21, vcc, 0, v35, vcc
	v_mfma_f32_16x16x32_bf16 v[4:7], v[16:19], v[108:111], v[4:7]
	v_add_co_u32_e32 v20, vcc, 0x20000, v34
	s_nop 1
	v_addc_co_u32_e32 v21, vcc, 0, v35, vcc
	v_mfma_f32_16x16x32_bf16 v[8:11], v[16:19], v[112:115], v[8:11]
	v_add_co_u32_e32 v20, vcc, 0x30000, v34
	s_nop 1
	v_addc_co_u32_e32 v21, vcc, 0, v35, vcc
	v_mfma_f32_16x16x32_bf16 v[12:15], v[16:19], v[116:119], v[12:15]
	v_or_b32_e32 v20, s35, v26
	v_ashrrev_i32_e32 v21, 31, v20
	s_and_saveexec_b64 s[36:37], s[6:7]
	s_xor_b64 s[36:37], exec, s[36:37]
	s_cbranch_execz .LBB0_323
	s_ashr_i32 s35, s35, 6
	v_mov_b32_e32 v16, 0x2230
	v_mad_i64_i32 v[16:17], s[56:57], s35, v16, v[28:29]
	v_mov_b32_e32 v31, v161
	v_lshl_add_u64 v[16:17], v[16:17], 0, v[30:31]
	global_load_dwordx4 v[16:19], v[16:17], off

; DI unsigned cvtpk(float lo, float hi) { return pg8::cvt_pk_bf16(lo, hi); }
; DI void compress_item(const Args& a, int l, int item, unsigned char* lds, int tid) {
;     ...
;     for (int ks = 0; ks < 8; ++ks) { const int kk = wave * 256 + ks * 32 + kq * 8, li = kk >> 6, d0 = kk & 63; bf16x8 af;
;         if (r < 15) af = *(const bf16x8*)(arow + (size_t)li * ZP + d0);
;         else { const f32x4 p0 = *(const f32x4*)(pe + kk), p1 = *(const f32x4*)(pe + kk + 4); u32x4 w; w.x = cvtpk(p0[0], p0[1]); w.y = cvtpk(p0[2], p0[3]); w.z = cvtpk(p1[0], p1[1]); w.w = cvtpk(p1[2], p1[3]); af = __builtin_bit_cast(bf16x8, w); }
; #pragma unroll
;         for (int ct = 0; ct < 4; ++ct) { const bf16x8 bfr = *(const bf16x8*)(wrow + (size_t)ct * 16 * 2048 + kk); acc[ct] = __builtin_amdgcn_mfma_f32_16x16x32_bf16(af, bfr, acc[ct], 0, 0, 0); } }
.LBB0_325:
	s_or_b64 exec, exec, s[36:37]
	v_lshl_add_u64 v[34:35], v[20:21], 1, v[24:25]
	s_or_b32 s35, s34, 0xa0
	s_waitcnt vmcnt(0)
	v_mfma_f32_16x16x32_bf16 v[0:3], v[16:19], v[120:123], v[0:3]
	v_add_co_u32_e32 v20, vcc, 0x10000, v34
	s_nop 1
	v_addc_co_u32_e32 v21, vcc, 0, v35, vcc
	v_mfma_f32_16x16x32_bf16 v[4:7], v[16:19], v[124:127], v[4:7]
	v_add_co_u32_e32 v20, vcc, 0x20000, v34
	s_nop 1
	v_addc_co_u32_e32 v21, vcc, 0, v35, vcc
	v_mfma_f32_16x16x32_bf16 v[8:11], v[16:19], v[128:131], v[8:11]
	v_add_co_u32_e32 v20, vcc, 0x30000, v34
	s_nop 1
	v_addc_co_u32_e32 v21, vcc, 0, v35, vcc
	v_mfma_f32_16x16x32_bf16 v[12:15], v[16:19], v[132:135], v[12:15]
	v_or_b32_e32 v16, s35, v26
	v_ashrrev_i32_e32 v17, 31, v16
	s_and_saveexec_b64 s[36:37], s[6:7]
	s_xor_b64 s[36:37], exec, s[36:37]
	s_cbranch_execz .LBB0_327
	v_and_b32_e32 v20, 56, v16
	s_ashr_i32 s35, s35, 6
	v_mov_b32_e32 v18, 0x2230
	v_mad_i64_i32 v[18:19], s[56:57], s35, v18, v[28:29]
	v_lshlrev_b32_e32 v160, 1, v20
	v_lshl_add_u64 v[18:19], v[18:19], 0, v[160:161]
	global_load_dwordx4 v[20:23], v[18:19], off

; DI unsigned cvtpk(float lo, float hi) { return pg8::cvt_pk_bf16(lo, hi); }
; DI void compress_item(const Args& a, int l, int item, unsigned char* lds, int tid) {
;     ...
;     for (int ks = 0; ks < 8; ++ks) { const int kk = wave * 256 + ks * 32 + kq * 8, li = kk >> 6, d0 = kk & 63; bf16x8 af;
;         if (r < 15) af = *(const bf16x8*)(arow + (size_t)li * ZP + d0);
;         else { const f32x4 p0 = *(const f32x4*)(pe + kk), p1 = *(const f32x4*)(pe + kk + 4); u32x4 w; w.x = cvtpk(p0[0], p0[1]); w.y = cvtpk(p0[2], p0[3]); w.z = cvtpk(p1[0], p1[1]); w.w = cvtpk(p1[2], p1[3]); af = __builtin_bit_cast(bf16x8, w); }
; #pragma unroll
;         for (int ct = 0; ct < 4; ++ct) { const bf16x8 bfr = *(const bf16x8*)(wrow + (size_t)ct * 16 * 2048 + kk); acc[ct] = __builtin_amdgcn_mfma_f32_16x16x32_bf16(af, bfr, acc[ct], 0, 0, 0); } }
.LBB0_329:
	s_or_b64 exec, exec, s[36:37]
	v_lshl_add_u64 v[34:35], v[16:17], 1, v[24:25]
	s_or_b32 s35, s34, 0xc0
	s_waitcnt vmcnt(0)
	v_mfma_f32_16x16x32_bf16 v[0:3], v[20:23], v[136:139], v[0:3]
	v_add_co_u32_e32 v16, vcc, 0x10000, v34
	s_nop 1
	v_addc_co_u32_e32 v17, vcc, 0, v35, vcc
	v_mfma_f32_16x16x32_bf16 v[4:7], v[20:23], v[140:143], v[4:7]
	v_add_co_u32_e32 v16, vcc, 0x20000, v34
	s_nop 1
	v_addc_co_u32_e32 v17, vcc, 0, v35, vcc
	v_mfma_f32_16x16x32_bf16 v[16:19], v[20:23], v[148:151], v[8:11]
	s_nop 2
	v_add_co_u32_e32 v8, vcc, 0x30000, v34
	s_nop 1
	v_addc_co_u32_e32 v9, vcc, 0, v35, vcc
	v_mfma_f32_16x16x32_bf16 v[12:15], v[20:23], v[152:155], v[12:15]
	v_or_b32_e32 v8, s35, v26
	v_ashrrev_i32_e32 v9, 31, v8
	s_and_saveexec_b64 s[36:37], s[6:7]
	s_xor_b64 s[36:37], exec, s[36:37]
	s_cbranch_execz .LBB0_331
	s_ashr_i32 s35, s35, 6
	v_mov_b32_e32 v10, 0x2230
	v_mad_i64_i32 v[10:11], s[56:57], s35, v10, v[28:29]
	v_mov_b32_e32 v31, v161
	v_lshl_add_u64 v[10:11], v[10:11], 0, v[30:31]
	global_load_dwordx4 v[20:23], v[10:11], off

; DI unsigned cvtpk(float lo, float hi) { return pg8::cvt_pk_bf16(lo, hi); }
; DI void compress_item(const Args& a, int l, int item, unsigned char* lds, int tid) {
;     ...
;     for (int ks = 0; ks < 8; ++ks) { const int kk = wave * 256 + ks * 32 + kq * 8, li = kk >> 6, d0 = kk & 63; bf16x8 af;
;         if (r < 15) af = *(const bf16x8*)(arow + (size_t)li * ZP + d0);
;         else { const f32x4 p0 = *(const f32x4*)(pe + kk), p1 = *(const f32x4*)(pe + kk + 4); u32x4 w; w.x = cvtpk(p0[0], p0[1]); w.y = cvtpk(p0[2], p0[3]); w.z = cvtpk(p1[0], p1[1]); w.w = cvtpk(p1[2], p1[3]); af = __builtin_bit_cast(bf16x8, w); }
; #pragma unroll
;         for (int ct = 0; ct < 4; ++ct) { const bf16x8 bfr = *(const bf16x8*)(wrow + (size_t)ct * 16 * 2048 + kk); acc[ct] = __builtin_amdgcn_mfma_f32_16x16x32_bf16(af, bfr, acc[ct], 0, 0, 0); } }
.LBB0_333:
	s_or_b64 exec, exec, s[36:37]
	v_lshl_add_u64 v[30:31], v[8:9], 1, v[24:25]
	s_or_b32 s35, s34, 0xe0
	s_waitcnt vmcnt(0)
	v_mfma_f32_16x16x32_bf16 v[8:11], v[20:23], v[156:159], v[0:3]
	s_nop 2
	v_add_co_u32_e32 v0, vcc, 0x10000, v30
	s_nop 1
	v_addc_co_u32_e32 v1, vcc, 0, v31, vcc
	v_mfma_f32_16x16x32_bf16 v[0:3], v[20:23], v[168:171], v[4:7]
	s_nop 2
	v_add_co_u32_e32 v4, vcc, 0x20000, v30
	s_nop 1
	v_addc_co_u32_e32 v5, vcc, 0, v31, vcc
	v_mfma_f32_16x16x32_bf16 v[4:7], v[20:23], v[172:175], v[16:19]
	s_nop 2
	v_add_co_u32_e32 v16, vcc, 0x30000, v30
	s_nop 1
	v_addc_co_u32_e32 v17, vcc, 0, v31, vcc
	v_mfma_f32_16x16x32_bf16 v[12:15], v[20:23], v[176:179], v[12:15]
	v_or_b32_e32 v20, s35, v26
	v_ashrrev_i32_e32 v21, 31, v20
	s_and_saveexec_b64 s[36:37], s[6:7]
	s_xor_b64 s[6:7], exec, s[36:37]
	s_cbranch_execz .LBB0_335
	v_and_b32_e32 v18, 56, v20
	s_ashr_i32 s35, s35, 6
	v_mov_b32_e32 v16, 0x2230
	v_mad_i64_i32 v[16:17], s[36:37], s35, v16, v[28:29]
	v_lshlrev_b32_e32 v160, 1, v18
	v_lshl_add_u64 v[16:17], v[16:17], 0, v[160:161]
	global_load_dwordx4 v[16:19], v[16:17], off

; DI void compress_item(const Args& a, int l, int item, unsigned char* lds, int tid) {
;     ...
;         for (int ct = 0; ct < 4; ++ct) { const bf16x8 bfr = *(const bf16x8*)(wrow + (size_t)ct * 16 * 2048 + kk); acc[ct] = __builtin_amdgcn_mfma_f32_16x16x32_bf16(af, bfr, acc[ct], 0, 0, 0); } }
; #pragma unroll
;     for (int ct = 0; ct < 4; ++ct)
; #pragma unroll
;         for (int i = 0; i < 4; ++i) part[wave * 1024 + (4 * kq + i) * 64 + ct * 16 + r] = acc[ct][i];
;     __syncthreads();
;     { float s0 = 0.f, s1 = 0.f;
; #pragma unroll
;       for (int w = 0; w < 8; ++w) { s0 += part[w * 1024 + tid]; s1 += part[w * 1024 + 512 + tid]; }
;       hs[tid] = s0; hs[512 + tid] = s1; }
;     __syncthreads();
;     { const float b0 = hs[15 * 64 + (tid & 63)]; const float x0 = hs[tid] + b0, x1 = hs[512 + tid] + b0;
;       __syncthreads();
;       hs[tid] = x0 / (1.0f + __expf(-x0)); hs[512 + tid] = x1 / (1.0f + __expf(-x1)); }
;     __syncthreads();
;     { const int r0 = wave, r1 = wave + 8; float o0 = 0.f, o1 = 0.f;
; #pragma unroll
;       for (int k16 = 0; k16 < 4; ++k16) { float wv[16];
; #pragma unroll
;           for (int k = 0; k < 16; ++k) wv[k] = w2[(k16 * 16 + k) * 64 + lane];
; #pragma unroll
;           for (int k = 0; k < 16; ++k) { o0 += hs[r0 * 64 + k16 * 16 + k] * wv[k]; o1 += hs[r1 * 64 + k16 * 16 + k] * wv[k]; } }
.LBB0_337:
	s_or_b64 exec, exec, s[6:7]
	v_lshl_add_u64 v[20:21], v[20:21], 1, v[24:25]
	s_mov_b32 s6, 0x10000
	v_readlane_b32 s36, v253, 35
	s_lshl_b64 s[0:1], s[0:1], 14
	v_readlane_b32 s50, v253, 49
	v_readlane_b32 s51, v253, 50
	s_add_u32 s0, s50, s0
	s_addc_u32 s1, s51, s1
	v_and_b32_e32 v22, 63, v146
	v_lshlrev_b32_e32 v160, 2, v22
	v_readlane_b32 s37, v253, 36
	v_readlane_b32 s38, v253, 37
	v_readlane_b32 s39, v253, 38
	v_readlane_b32 s40, v253, 39
	v_readlane_b32 s41, v253, 40
	v_readlane_b32 s42, v253, 41
	v_readlane_b32 s43, v253, 42
	v_readlane_b32 s44, v253, 43
	v_readlane_b32 s45, v253, 44
	v_readlane_b32 s46, v253, 45
	v_readlane_b32 s47, v253, 46
	v_readlane_b32 s48, v253, 47
	v_readlane_b32 s49, v253, 48
	s_waitcnt vmcnt(0)
	v_mfma_f32_16x16x32_bf16 v[8:11], v[16:19], v[180:183], v[8:11]
	v_add_co_u32_e32 v24, vcc, s6, v20
	s_mov_b32 s6, 0x20000
	s_nop 0
	v_addc_co_u32_e32 v25, vcc, 0, v21, vcc
	v_mfma_f32_16x16x32_bf16 v[0:3], v[16:19], v[184:187], v[0:3]
	v_add_co_u32_e32 v24, vcc, s6, v20
	s_mov_b32 s6, 0x30000
	s_nop 0
	v_addc_co_u32_e32 v25, vcc, 0, v21, vcc
	v_add_co_u32_e32 v20, vcc, s6, v20
	s_lshl_b32 s6, s8, 12
	s_nop 0
	v_addc_co_u32_e32 v21, vcc, 0, v21, vcc
	s_add_i32 s6, s6, 0
	v_mfma_f32_16x16x32_bf16 v[4:7], v[16:19], v[188:191], v[4:7]
	v_mfma_f32_16x16x32_bf16 v[12:15], v[16:19], v[192:195], v[12:15]
	v_lshlrev_b32_e32 v16, 10, v33
	v_lshlrev_b32_e32 v17, 2, v32
	v_add3_u32 v16, s6, v16, v17
	ds_write2_b32 v16, v8, v0 offset1:16
	ds_write2_b32 v16, v9, v1 offset0:64 offset1:80
	ds_write2_b32 v16, v10, v2 offset0:128 offset1:144
	ds_write2_b32 v16, v11, v3 offset0:192 offset1:208
	s_nop 0
	ds_write2_b32 v16, v4, v12 offset0:32 offset1:48
	ds_write2_b32 v16, v5, v13 offset0:96 offset1:112
	ds_write2_b32 v16, v6, v14 offset0:160 offset1:176
	ds_write2_b32 v16, v7, v15 offset0:224 offset1:240
	v_lshl_add_u32 v0, v146, 2, 0
	s_waitcnt lgkmcnt(0)
	s_barrier
	ds_read2st64_b32 v[2:3], v0 offset1:8
	s_waitcnt lgkmcnt(0)
	v_add_f32_e32 v1, 0, v2
	v_add_f32_e32 v4, 0, v3
	ds_read2st64_b32 v[2:3], v0 offset0:16 offset1:24
	s_waitcnt lgkmcnt(0)
	v_add_f32_e32 v1, v1, v2
	v_add_f32_e32 v4, v4, v3
	ds_read2st64_b32 v[2:3], v0 offset0:32 offset1:40
	s_waitcnt lgkmcnt(0)
	v_add_f32_e32 v1, v1, v2
	v_add_f32_e32 v4, v4, v3
	ds_read2st64_b32 v[2:3], v0 offset0:48 offset1:56
	s_waitcnt lgkmcnt(0)
	v_add_f32_e32 v1, v1, v2
	v_add_f32_e32 v4, v4, v3
	ds_read2st64_b32 v[2:3], v0 offset0:64 offset1:72
	s_waitcnt lgkmcnt(0)
	v_add_f32_e32 v1, v1, v2
	v_add_f32_e32 v4, v4, v3
	ds_read2st64_b32 v[2:3], v0 offset0:80 offset1:88
	s_waitcnt lgkmcnt(0)
	v_add_f32_e32 v1, v1, v2
	v_add_f32_e32 v4, v4, v3
	ds_read2st64_b32 v[2:3], v0 offset0:96 offset1:104
	s_waitcnt lgkmcnt(0)
	v_add_f32_e32 v1, v1, v2
	v_add_f32_e32 v4, v4, v3
	ds_read2st64_b32 v[2:3], v0 offset0:112 offset1:120
	s_waitcnt lgkmcnt(0)
	v_add_f32_e32 v1, v1, v2
	v_add_f32_e32 v2, v4, v3
	ds_write2st64_b32 v0, v1, v2 offset0:128 offset1:136
	v_add_u32_e32 v1, 0, v160
	s_waitcnt lgkmcnt(0)
	s_barrier
	ds_read_b32 v1, v1 offset:36608
	ds_read2st64_b32 v[2:3], v0 offset0:128 offset1:136
	s_waitcnt lgkmcnt(0)
	s_barrier
	v_add_f32_e32 v2, v1, v2
	v_add_f32_e32 v1, v1, v3
	v_mul_f32_e32 v3, 0xbfb8aa3b, v2
	v_exp_f32_e32 v3, v3
	s_nop 0
	v_add_f32_e32 v3, 1.0, v3
	v_div_scale_f32 v4, s[6:7], v3, v3, v2
	v_rcp_f32_e32 v5, v4
	s_nop 0
	v_fma_f32 v6, -v4, v5, 1.0
	v_fmac_f32_e32 v5, v6, v5
	v_div_scale_f32 v6, vcc, v2, v3, v2
	v_mul_f32_e32 v7, v6, v5
	v_fma_f32 v8, -v4, v7, v6
	v_fmac_f32_e32 v7, v8, v5
	v_fma_f32 v4, -v4, v7, v6
	v_div_fmas_f32 v4, v4, v5, v7
	v_div_fixup_f32 v2, v4, v3, v2
	v_mul_f32_e32 v3, 0xbfb8aa3b, v1
	v_exp_f32_e32 v3, v3
	s_nop 0
	v_add_f32_e32 v3, 1.0, v3
	v_div_scale_f32 v4, s[6:7], v3, v3, v1
	v_rcp_f32_e32 v5, v4
	s_and_b32 s7, s59, 0x3fffffc0
	s_lshl_b32 s7, s7, 2
	s_add_i32 s7, s7, 0
	v_fma_f32 v6, -v4, v5, 1.0
	v_fmac_f32_e32 v5, v6, v5
	v_div_scale_f32 v6, vcc, v1, v3, v1
	v_mul_f32_e32 v7, v6, v5
	v_fma_f32 v8, -v4, v7, v6
	v_fmac_f32_e32 v7, v8, v5
	v_fma_f32 v4, -v4, v7, v6
	v_div_fmas_f32 v4, v4, v5, v7
	v_div_fixup_f32 v1, v4, v3, v1
	ds_write2st64_b32 v0, v2, v1 offset0:128 offset1:136
	s_waitcnt lgkmcnt(0)
	s_barrier
	global_load_dword v4, v160, s[0:1]
	global_load_dword v23, v160, s[0:1] offset:256
	global_load_dword v40, v160, s[0:1] offset:512
	global_load_dword v41, v160, s[0:1] offset:768
	global_load_dword v42, v160, s[0:1] offset:1024
	global_load_dword v43, v160, s[0:1] offset:1280
	global_load_dword v44, v160, s[0:1] offset:1536
	global_load_dword v45, v160, s[0:1] offset:1792
	global_load_dword v46, v160, s[0:1] offset:2048
	global_load_dword v47, v160, s[0:1] offset:2304
	global_load_dword v48, v160, s[0:1] offset:2560
	global_load_dword v49, v160, s[0:1] offset:2816
	global_load_dword v50, v160, s[0:1] offset:3072
	global_load_dword v51, v160, s[0:1] offset:3328
	global_load_dword v52, v160, s[0:1] offset:3584
	global_load_dword v53, v160, s[0:1] offset:3840
	v_mov_b32_e32 v3, s7
	ds_read_b128 v[6:9], v3 offset:32768
	ds_read_b128 v[10:13], v3 offset:32784
	ds_read_b128 v[14:17], v3 offset:32800
	ds_read_b128 v[18:21], v3 offset:32816
	s_add_i32 s6, s8, 8
	s_lshl_b32 s10, s6, 8
	s_add_i32 s10, s10, 0
	v_mov_b32_e32 v2, s10
	ds_read_b128 v[24:27], v2 offset:32768
	ds_read_b128 v[28:31], v2 offset:32784
	ds_read_b128 v[32:35], v2 offset:32800
	ds_read_b128 v[36:39], v2 offset:32816
	v_lshl_add_u64 v[0:1], s[0:1], 0, v[160:161]
	s_movk_i32 s0, 0x3000
	s_cmp_lg_u32 s9, 0
	s_waitcnt vmcnt(15) lgkmcnt(7)
	v_fma_f32 v5, v4, v6, 0
	s_waitcnt vmcnt(14)
	v_fmac_f32_e32 v5, v23, v7
	s_waitcnt vmcnt(13)
	v_fmac_f32_e32 v5, v40, v8
	s_waitcnt vmcnt(12)
; DI void compress_item(const Args& a, int l, int item, unsigned char* lds, int tid) {
;     ...
;     { const int r0 = wave, r1 = wave + 8; float o0 = 0.f, o1 = 0.f;
; #pragma unroll
;       for (int k16 = 0; k16 < 4; ++k16) { float wv[16];
; #pragma unroll
;           for (int k = 0; k < 16; ++k) wv[k] = w2[(k16 * 16 + k) * 64 + lane];
; #pragma unroll
;           for (int k = 0; k < 16; ++k) { o0 += hs[r0 * 64 + k16 * 16 + k] * wv[k]; o1 += hs[r1 * 64 + k16 * 16 + k] * wv[k]; } }
	v_fmac_f32_e32 v5, v41, v9
	s_waitcnt vmcnt(11) lgkmcnt(6)
	v_fmac_f32_e32 v5, v42, v10
	s_waitcnt vmcnt(10)
	v_fmac_f32_e32 v5, v43, v11
	s_waitcnt vmcnt(9)
	v_fmac_f32_e32 v5, v44, v12
	s_waitcnt lgkmcnt(3)
	v_fma_f32 v4, v4, v24, 0
	s_waitcnt vmcnt(8)
	v_fmac_f32_e32 v5, v45, v13
	v_fmac_f32_e32 v4, v23, v25
	s_waitcnt vmcnt(7)
	v_fmac_f32_e32 v5, v46, v14
	v_fmac_f32_e32 v4, v40, v26
	s_waitcnt vmcnt(6)
	v_fmac_f32_e32 v5, v47, v15
	v_fmac_f32_e32 v4, v41, v27
	s_waitcnt vmcnt(5)
	v_fmac_f32_e32 v5, v48, v16
	s_waitcnt lgkmcnt(2)
	v_fmac_f32_e32 v4, v42, v28
	s_waitcnt vmcnt(4)
	v_fmac_f32_e32 v5, v49, v17
	v_add_co_u32_e32 v6, vcc, s85, v0
	v_fmac_f32_e32 v4, v43, v29
	s_waitcnt vmcnt(3)
	v_fmac_f32_e32 v5, v50, v18
	v_addc_co_u32_e32 v7, vcc, 0, v1, vcc
	v_fmac_f32_e32 v4, v44, v30
	s_waitcnt vmcnt(2)
	v_fmac_f32_e32 v5, v51, v19
	v_add_co_u32_e32 v14, vcc, s89, v0
	v_fmac_f32_e32 v4, v45, v31
	s_waitcnt vmcnt(1)
	v_fmac_f32_e32 v5, v52, v20
	v_addc_co_u32_e32 v15, vcc, 0, v1, vcc
	s_waitcnt lgkmcnt(1)
	v_fmac_f32_e32 v4, v46, v32
	s_waitcnt vmcnt(0)
	v_fmac_f32_e32 v5, v53, v21
	global_load_dword v16, v[14:15], off offset:-4096
	global_load_dword v17, v[6:7], off offset:256
	global_load_dword v18, v[6:7], off offset:512
	global_load_dword v19, v[6:7], off offset:768
	global_load_dword v20, v[6:7], off offset:1024
	global_load_dword v21, v[6:7], off offset:1280
	global_load_dword v23, v[6:7], off offset:1536
	global_load_dword v24, v[6:7], off offset:1792
	global_load_dword v25, v[6:7], off offset:2048
	global_load_dword v26, v[6:7], off offset:2304
	global_load_dword v27, v[6:7], off offset:2560
	global_load_dword v28, v[6:7], off offset:2816
	global_load_dword v29, v[6:7], off offset:3072
	global_load_dword v30, v[6:7], off offset:3328
	global_load_dword v31, v[6:7], off offset:3584
	global_load_dword v32, v[6:7], off offset:3840
	v_fmac_f32_e32 v4, v47, v33
	v_fmac_f32_e32 v4, v48, v34
	v_fmac_f32_e32 v4, v49, v35
	ds_read_b128 v[6:9], v3 offset:32832
	ds_read_b128 v[10:13], v2 offset:32832
	s_waitcnt lgkmcnt(2)
	v_fmac_f32_e32 v4, v50, v36
	v_fmac_f32_e32 v4, v51, v37
	v_fmac_f32_e32 v4, v52, v38
	v_fmac_f32_e32 v4, v53, v39
	s_waitcnt vmcnt(15) lgkmcnt(1)
	v_fmac_f32_e32 v5, v16, v6
	s_waitcnt lgkmcnt(0)
	v_fmac_f32_e32 v4, v16, v10
	s_waitcnt vmcnt(14)
	v_fmac_f32_e32 v5, v17, v7
	v_fmac_f32_e32 v4, v17, v11
	s_waitcnt vmcnt(13)
	v_fmac_f32_e32 v5, v18, v8
	v_fmac_f32_e32 v4, v18, v12
	s_waitcnt vmcnt(12)
	v_fmac_f32_e32 v5, v19, v9
	v_fmac_f32_e32 v4, v19, v13
	ds_read_b128 v[6:9], v3 offset:32848
	ds_read_b128 v[10:13], v2 offset:32848
	s_waitcnt vmcnt(11) lgkmcnt(1)
	v_fmac_f32_e32 v5, v20, v6
	s_waitcnt lgkmcnt(0)
	v_fmac_f32_e32 v4, v20, v10
	s_waitcnt vmcnt(10)
	v_fmac_f32_e32 v5, v21, v7
	v_fmac_f32_e32 v4, v21, v11
	s_waitcnt vmcnt(9)
	v_fmac_f32_e32 v5, v23, v8
	v_fmac_f32_e32 v4, v23, v12
	s_waitcnt vmcnt(8)
	v_fmac_f32_e32 v5, v24, v9
	v_fmac_f32_e32 v4, v24, v13
	ds_read_b128 v[6:9], v3 offset:32864
	ds_read_b128 v[10:13], v2 offset:32864
	s_waitcnt vmcnt(7) lgkmcnt(1)
	v_fmac_f32_e32 v5, v25, v6
	s_waitcnt lgkmcnt(0)
	v_fmac_f32_e32 v4, v25, v10
	s_waitcnt vmcnt(6)
	v_fmac_f32_e32 v5, v26, v7
	v_fmac_f32_e32 v4, v26, v11
	s_waitcnt vmcnt(5)
	v_fmac_f32_e32 v5, v27, v8
	v_fmac_f32_e32 v4, v27, v12
	s_waitcnt vmcnt(4)
	v_fmac_f32_e32 v5, v28, v9
	v_fmac_f32_e32 v4, v28, v13
	ds_read_b128 v[6:9], v3 offset:32880
	ds_read_b128 v[10:13], v2 offset:32880
	s_waitcnt vmcnt(3) lgkmcnt(1)
	v_fmac_f32_e32 v5, v29, v6
	s_waitcnt lgkmcnt(0)
	v_fmac_f32_e32 v4, v29, v10
	s_waitcnt vmcnt(2)
	v_fmac_f32_e32 v5, v30, v7
	v_fmac_f32_e32 v4, v30, v11
	s_waitcnt vmcnt(1)
	v_fmac_f32_e32 v5, v31, v8
	v_fmac_f32_e32 v4, v31, v12
	global_load_dword v16, v[14:15], off
	global_load_dword v17, v[14:15], off offset:256
	global_load_dword v18, v[14:15], off offset:512
	global_load_dword v19, v[14:15], off offset:768
	global_load_dword v20, v[14:15], off offset:1024
	global_load_dword v21, v[14:15], off offset:1280
	global_load_dword v23, v[14:15], off offset:1536
	global_load_dword v24, v[14:15], off offset:1792
	global_load_dword v25, v[14:15], off offset:2048
	global_load_dword v26, v[14:15], off offset:2304
	global_load_dword v27, v[14:15], off offset:2560
	global_load_dword v28, v[14:15], off offset:2816
	global_load_dword v29, v[14:15], off offset:3072
	global_load_dword v30, v[14:15], off offset:3328
	global_load_dword v31, v[14:15], off offset:3584
	s_nop 0
	global_load_dword v14, v[14:15], off offset:3840
	s_waitcnt vmcnt(16)
	v_fmac_f32_e32 v5, v32, v9
	v_fmac_f32_e32 v4, v32, v13
	ds_read_b128 v[6:9], v3 offset:32896
	ds_read_b128 v[10:13], v2 offset:32896
	s_waitcnt vmcnt(15) lgkmcnt(1)
; DI bf16_t f2bf(float f) { return (bf16_t)(cvtpk(f, 0.f) & 0xffffu); }
; DI void compress_item(const Args& a, int l, int item, unsigned char* lds, int tid) {
;     ...
;     { const int r0 = wave, r1 = wave + 8; float o0 = 0.f, o1 = 0.f;
; #pragma unroll
;       for (int k16 = 0; k16 < 4; ++k16) { float wv[16];
; #pragma unroll
;           for (int k = 0; k < 16; ++k) wv[k] = w2[(k16 * 16 + k) * 64 + lane];
; #pragma unroll
;           for (int k = 0; k < 16; ++k) { o0 += hs[r0 * 64 + k16 * 16 + k] * wv[k]; o1 += hs[r1 * 64 + k16 * 16 + k] * wv[k]; } }
;       if (j == 0) { const float gg = g1[lane];
;           { const float q = wave_sum(o0 * o0); KC[(((size_t)b * 2 + g) * 256 + 15 * tix + r0) * 64 + lane] = f2bf(o0 * rsqrtf(q * (1.0f / 64.0f) + 1e-6f) * gg); }
;           { const float q = wave_sum(o1 * o1); if (r1 < 15) KC[(((size_t)b * 2 + g) * 256 + 15 * tix + r1) * 64 + lane] = f2bf(o1 * rsqrtf(q * (1.0f / 64.0f) + 1e-6f) * gg); }
;           if (tix == 16 && wave == 0) KC[(((size_t)b * 2 + g) * 256 + 255) * 64 + lane] = 0;
;       } else {
;           VCT[(((size_t)b * 2 + g) * 64 + lane) * 256 + 15 * tix + r0] = f2bf(o0);
;           if (r1 < 15) VCT[(((size_t)b * 2 + g) * 64 + lane) * 256 + 15 * tix + r1] = f2bf(o1);
;           if (tix == 16 && wave == 0) VCT[(((size_t)b * 2 + g) * 64 + lane) * 256 + 255] = 0;
	v_fmac_f32_e32 v5, v16, v6
	s_waitcnt lgkmcnt(0)
	v_fmac_f32_e32 v4, v16, v10
	s_waitcnt vmcnt(14)
	v_fmac_f32_e32 v5, v17, v7
	v_fmac_f32_e32 v4, v17, v11
	s_waitcnt vmcnt(13)
	v_fmac_f32_e32 v5, v18, v8
	v_fmac_f32_e32 v4, v18, v12
	s_waitcnt vmcnt(12)
	v_fmac_f32_e32 v5, v19, v9
	v_fmac_f32_e32 v4, v19, v13
	ds_read_b128 v[6:9], v3 offset:32912
	ds_read_b128 v[10:13], v2 offset:32912
	s_waitcnt vmcnt(11) lgkmcnt(1)
	v_fmac_f32_e32 v5, v20, v6
	s_waitcnt lgkmcnt(0)
	v_fmac_f32_e32 v4, v20, v10
	s_waitcnt vmcnt(10)
	v_fmac_f32_e32 v5, v21, v7
	v_fmac_f32_e32 v4, v21, v11
	s_waitcnt vmcnt(9)
	v_fmac_f32_e32 v5, v23, v8
	v_fmac_f32_e32 v4, v23, v12
	s_waitcnt vmcnt(8)
	v_fmac_f32_e32 v5, v24, v9
	v_fmac_f32_e32 v4, v24, v13
	ds_read_b128 v[6:9], v3 offset:32928
	ds_read_b128 v[10:13], v2 offset:32928
	v_add_co_u32_e32 v20, vcc, s0, v0
	s_mov_b64 s[0:1], -1
	s_waitcnt vmcnt(7) lgkmcnt(1)
	v_fmac_f32_e32 v5, v25, v6
	s_waitcnt lgkmcnt(0)
	v_fmac_f32_e32 v4, v25, v10
	s_waitcnt vmcnt(6)
	v_fmac_f32_e32 v5, v26, v7
	v_fmac_f32_e32 v4, v26, v11
	s_waitcnt vmcnt(5)
	v_fmac_f32_e32 v5, v27, v8
	v_fmac_f32_e32 v4, v27, v12
	s_waitcnt vmcnt(4)
	v_fmac_f32_e32 v5, v28, v9
	v_fmac_f32_e32 v4, v28, v13
	ds_read_b128 v[6:9], v3 offset:32944
	ds_read_b128 v[10:13], v2 offset:32944
	v_addc_co_u32_e32 v21, vcc, 0, v1, vcc
	s_waitcnt vmcnt(3) lgkmcnt(1)
	v_fmac_f32_e32 v5, v29, v6
	s_waitcnt lgkmcnt(0)
	v_fmac_f32_e32 v4, v29, v10
	s_waitcnt vmcnt(2)
	v_fmac_f32_e32 v5, v30, v7
	v_fmac_f32_e32 v4, v30, v11
	s_waitcnt vmcnt(1)
	v_fmac_f32_e32 v5, v31, v8
	v_fmac_f32_e32 v4, v31, v12
	s_waitcnt vmcnt(0)
	v_fmac_f32_e32 v5, v14, v9
	v_fmac_f32_e32 v4, v14, v13
	global_load_dword v16, v[20:21], off
	global_load_dword v15, v[20:21], off offset:256
	global_load_dword v14, v[20:21], off offset:512
	global_load_dword v13, v[20:21], off offset:768
	global_load_dword v8, v[20:21], off offset:1024
	global_load_dword v7, v[20:21], off offset:1280
	global_load_dword v6, v[20:21], off offset:1536
	global_load_dword v1, v[20:21], off offset:1792
	global_load_dword v0, v[20:21], off offset:2048
	global_load_dword v17, v[20:21], off offset:2304
	global_load_dword v18, v[20:21], off offset:2560
	global_load_dword v19, v[20:21], off offset:2816
	global_load_dword v12, v[20:21], off offset:3072
	global_load_dword v11, v[20:21], off offset:3328
	global_load_dword v10, v[20:21], off offset:3584
	global_load_dword v9, v[20:21], off offset:3840
	ds_read_b128 v[24:27], v3 offset:32960
	ds_read_b128 v[28:31], v2 offset:32960
	s_waitcnt vmcnt(15) lgkmcnt(1)
	v_fmac_f32_e32 v5, v16, v24
	s_waitcnt lgkmcnt(0)
	v_fmac_f32_e32 v4, v16, v28
	s_waitcnt vmcnt(14)
	v_fmac_f32_e32 v5, v15, v25
	v_fmac_f32_e32 v4, v15, v29
	s_waitcnt vmcnt(13)
	v_fmac_f32_e32 v5, v14, v26
	v_fmac_f32_e32 v4, v14, v30
	s_waitcnt vmcnt(12)
	v_fmac_f32_e32 v5, v13, v27
	v_fmac_f32_e32 v4, v13, v31
	ds_read_b128 v[24:27], v3 offset:32976
	ds_read_b128 v[28:31], v2 offset:32976
	s_waitcnt vmcnt(11) lgkmcnt(1)
	v_fmac_f32_e32 v5, v8, v24
	s_waitcnt lgkmcnt(0)
	v_fmac_f32_e32 v4, v8, v28
	s_waitcnt vmcnt(10)
	v_fmac_f32_e32 v5, v7, v25
	v_fmac_f32_e32 v4, v7, v29
	s_waitcnt vmcnt(9)
	v_fmac_f32_e32 v5, v6, v26
	v_fmac_f32_e32 v4, v6, v30
	s_waitcnt vmcnt(8)
	v_fmac_f32_e32 v5, v1, v27
	v_fmac_f32_e32 v4, v1, v31
	ds_read_b128 v[24:27], v3 offset:32992
	ds_read_b128 v[28:31], v2 offset:32992
	s_waitcnt vmcnt(7) lgkmcnt(1)
	v_fmac_f32_e32 v5, v0, v24
	s_waitcnt lgkmcnt(0)
	v_fmac_f32_e32 v4, v0, v28
	s_waitcnt vmcnt(6)
	v_fmac_f32_e32 v5, v17, v25
	v_fmac_f32_e32 v4, v17, v29
	ds_read_b128 v[14:17], v3 offset:33008
	ds_read_b128 v[0:3], v2 offset:33008
	s_waitcnt vmcnt(5)
	v_fmac_f32_e32 v5, v18, v26
	v_fmac_f32_e32 v4, v18, v30
	s_waitcnt vmcnt(4)
	v_fmac_f32_e32 v5, v19, v27
	v_fmac_f32_e32 v4, v19, v31
	s_waitcnt vmcnt(3) lgkmcnt(1)
	v_fmac_f32_e32 v5, v12, v14
	s_waitcnt lgkmcnt(0)
	v_fmac_f32_e32 v4, v12, v0
	s_waitcnt vmcnt(2)
	v_fmac_f32_e32 v5, v11, v15
	v_fmac_f32_e32 v4, v11, v1
	s_waitcnt vmcnt(1)
	v_fmac_f32_e32 v5, v10, v16
	v_fmac_f32_e32 v4, v10, v2
	s_waitcnt vmcnt(0)
	v_fmac_f32_e32 v5, v9, v17
	v_fmac_f32_e32 v4, v9, v3
	s_cbranch_scc0 .LBB0_343
	s_lshl_b32 s0, s52, 6
	s_lshl_b32 s1, s53, 7
	v_cvt_pk_bf16_f32 v6, v5, s0
	s_or_b32 s0, s1, s0
	v_or_b32_e32 v0, s0, v22
	v_readlane_b32 s0, v254, 48
	v_lshlrev_b32_e32 v0, 9, v0
	v_mov_b32_e32 v1, v161
	v_readlane_b32 s1, v254, 49
	s_lshl_b32 s80, s54, 1
	s_ashr_i32 s9, s8, 31
	v_lshl_add_u64 v[0:1], s[0:1], 0, v[0:1]
	v_lshl_add_u64 v[2:3], v[0:1], 0, s[80:81]
	v_lshl_add_u64 v[2:3], s[8:9], 1, v[2:3]
	s_cmp_gt_i32 s8, 6
	global_store_short v[2:3], v6, off
	s_cbranch_scc1 .LBB0_340
	v_cvt_pk_bf16_f32 v6, v4, s0
	global_store_short v[2:3], v6, off offset:16
